# v14 + MLA softmax VALU trim: per-lane max test with the cross-lane max only on the rare rescale path, per-lane row-sum accumulation reduced once at unit end
# speedup vs baseline: 1.0010x; 1.0010x over previous
.LBB0_786:
	s_bitcmp1_b32 s2, 0
	s_cselect_b32 s2, 0xa000, 0
	v_add_u32_e32 v96, s2, v95
	ds_read_b128 v[172:175], v96
	ds_read_b128 v[176:179], v96 offset:1024
	ds_read_b128 v[188:191], v96 offset:2048
	ds_read_b128 v[192:195], v96 offset:3072
	ds_read_b128 v[198:201], v96 offset:4096
	ds_read_b128 v[202:205], v96 offset:5120
	s_cmp_eq_u32 s5, 1
	s_cbranch_scc1 .Lmy_first
	s_waitcnt lgkmcnt(5)
	v_mfma_f32_32x32x16_bf16 v[64:79], v[172:175], v[82:85], 0
	ds_read_b128 v[172:175], v96 offset:6144
	v_max_f32_e32 v111, v218, v219
	v_max3_f32 v111, v111, v220, v221
	v_max3_f32 v111, v111, v222, v223
	v_max3_f32 v111, v111, v224, v225
	s_waitcnt lgkmcnt(5)
	v_mfma_f32_32x32x16_bf16 v[64:79], v[176:179], v[86:89], v[64:79]
	ds_read_b128 v[176:179], v96 offset:7168
	v_max3_f32 v111, v111, v226, v227
	v_max3_f32 v111, v111, v228, v229
	v_max3_f32 v111, v111, v230, v231
	v_max3_f32 v111, v111, v232, v233
	s_waitcnt lgkmcnt(5)
	v_mfma_f32_32x32x16_bf16 v[64:79], v[188:191], v[90:93], v[64:79]
	ds_read_b128 v[188:191], v96 offset:8192
	v_mul_f32_e32 v159, 0x3dd53b94, v111
	v_cmp_le_f32_e32 vcc, v159, v110
	s_cmp_eq_u64 vcc, exec
	s_cbranch_scc1 .LBB0_790
	v_mov_b32_e32 v159, v111
	s_nop 1
	v_permlane32_swap_b32_e32 v111, v159
	v_max_f32_e32 v111, v111, v159
	v_mul_f32_e32 v111, 0x3dd53b94, v111
	v_max_f32_e32 v110, v111, v111
	v_max_f32_e32 v111, v80, v80
	v_max_f32_e32 v111, v111, v110
	v_sub_f32_e32 v80, v80, v111
	v_exp_f32_e32 v80, v80
	v_xor_b32_e32 v110, 0x80000000, v111
	v_mul_f32_e32 v81, v81, v80
	v_pk_mul_f32 v[62:63], v[62:63], v[80:81] op_sel_hi:[1,0]
	v_pk_mul_f32 v[60:61], v[60:61], v[80:81] op_sel_hi:[1,0]
	v_pk_mul_f32 v[58:59], v[58:59], v[80:81] op_sel_hi:[1,0]
	v_pk_mul_f32 v[56:57], v[56:57], v[80:81] op_sel_hi:[1,0]
	v_pk_mul_f32 v[54:55], v[54:55], v[80:81] op_sel_hi:[1,0]
	v_pk_mul_f32 v[52:53], v[52:53], v[80:81] op_sel_hi:[1,0]
	v_pk_mul_f32 v[50:51], v[50:51], v[80:81] op_sel_hi:[1,0]
	v_pk_mul_f32 v[48:49], v[48:49], v[80:81] op_sel_hi:[1,0]
	v_pk_mul_f32 v[46:47], v[46:47], v[80:81] op_sel_hi:[1,0]
	v_pk_mul_f32 v[44:45], v[44:45], v[80:81] op_sel_hi:[1,0]
	v_pk_mul_f32 v[42:43], v[42:43], v[80:81] op_sel_hi:[1,0]
	v_pk_mul_f32 v[40:41], v[40:41], v[80:81] op_sel_hi:[1,0]
	v_pk_mul_f32 v[38:39], v[38:39], v[80:81] op_sel_hi:[1,0]
	v_pk_mul_f32 v[36:37], v[36:37], v[80:81] op_sel_hi:[1,0]
	v_pk_mul_f32 v[34:35], v[34:35], v[80:81] op_sel_hi:[1,0]
	v_pk_mul_f32 v[32:33], v[32:33], v[80:81] op_sel_hi:[1,0]
	v_pk_mul_f32 v[30:31], v[30:31], v[80:81] op_sel_hi:[1,0]
	v_pk_mul_f32 v[28:29], v[28:29], v[80:81] op_sel_hi:[1,0]
	v_pk_mul_f32 v[26:27], v[26:27], v[80:81] op_sel_hi:[1,0]
	v_pk_mul_f32 v[24:25], v[24:25], v[80:81] op_sel_hi:[1,0]
	v_pk_mul_f32 v[22:23], v[22:23], v[80:81] op_sel_hi:[1,0]
	v_pk_mul_f32 v[20:21], v[20:21], v[80:81] op_sel_hi:[1,0]
	v_pk_mul_f32 v[18:19], v[18:19], v[80:81] op_sel_hi:[1,0]
	v_pk_mul_f32 v[16:17], v[16:17], v[80:81] op_sel_hi:[1,0]
	v_pk_mul_f32 v[14:15], v[14:15], v[80:81] op_sel_hi:[1,0]
	v_pk_mul_f32 v[12:13], v[12:13], v[80:81] op_sel_hi:[1,0]
	v_pk_mul_f32 v[10:11], v[10:11], v[80:81] op_sel_hi:[1,0]
	v_pk_mul_f32 v[8:9], v[8:9], v[80:81] op_sel_hi:[1,0]
	v_pk_mul_f32 v[6:7], v[6:7], v[80:81] op_sel_hi:[1,0]
	v_pk_mul_f32 v[4:5], v[4:5], v[80:81] op_sel_hi:[1,0]
	v_pk_mul_f32 v[2:3], v[2:3], v[80:81] op_sel_hi:[1,0]
	v_pk_mul_f32 v[0:1], v[0:1], v[80:81] op_sel_hi:[1,0]
	v_mov_b32_e32 v80, v111
	s_branch .LBB0_791

.LBB0_791:
	s_waitcnt lgkmcnt(5)
	v_mfma_f32_32x32x16_bf16 v[64:79], v[192:195], v[112:115], v[64:79]
	ds_read_b128 v[192:195], v96 offset:9216
	v_fmamk_f32 v218, v218, 0x3dd53b94, v110
	v_fmamk_f32 v219, v219, 0x3dd53b94, v110
	v_exp_f32_e32 v218, v218
	v_fmamk_f32 v220, v220, 0x3dd53b94, v110
	v_exp_f32_e32 v219, v219
	s_waitcnt lgkmcnt(5)
	v_mfma_f32_32x32x16_bf16 v[64:79], v[198:201], v[116:119], v[64:79]
	ds_read_b128 v[198:201], v96 offset:10240
	v_add_f32_e32 v183, 0, v218
	v_fmamk_f32 v221, v221, 0x3dd53b94, v110
	v_exp_f32_e32 v220, v220
	v_add_f32_e32 v183, v219, v183
	v_fmamk_f32 v222, v222, 0x3dd53b94, v110
	s_waitcnt lgkmcnt(5)
	v_mfma_f32_32x32x16_bf16 v[64:79], v[202:205], v[120:123], v[64:79]
	ds_read_b128 v[202:205], v96 offset:11264
	v_exp_f32_e32 v221, v221
	v_add_f32_e32 v183, v220, v183
	v_fmamk_f32 v223, v223, 0x3dd53b94, v110
	v_exp_f32_e32 v222, v222
	v_add_f32_e32 v183, v221, v183
	s_waitcnt lgkmcnt(5)
	v_mfma_f32_32x32x16_bf16 v[64:79], v[172:175], v[124:127], v[64:79]
	ds_read_b128 v[172:175], v96 offset:20480
	v_fmamk_f32 v224, v224, 0x3dd53b94, v110
	v_exp_f32_e32 v223, v223
	v_add_f32_e32 v183, v222, v183
	v_fmamk_f32 v225, v225, 0x3dd53b94, v110
	v_exp_f32_e32 v224, v224
	s_waitcnt lgkmcnt(5)
	v_mfma_f32_32x32x16_bf16 v[64:79], v[176:179], v[128:131], v[64:79]
	ds_read_b128 v[176:179], v96 offset:21504
	v_add_f32_e32 v183, v223, v183
	v_exp_f32_e32 v225, v225
	v_add_f32_e32 v183, v224, v183
	v_add_f32_e32 v183, v225, v183
	v_fmamk_f32 v159, v226, 0x3dd53b94, v110
	s_waitcnt lgkmcnt(5)
	v_mfma_f32_32x32x16_bf16 v[64:79], v[188:191], v[132:135], v[64:79]
	ds_read_b128 v[188:191], v96 offset:22528
	v_fmamk_f32 v111, v227, 0x3dd53b94, v110
	v_fmamk_f32 v165, v228, 0x3dd53b94, v110
	v_fmamk_f32 v166, v229, 0x3dd53b94, v110
	v_cvt_pk_bf16_f32 v218, v218, v219
	v_cvt_pk_bf16_f32 v219, v220, v221
	s_waitcnt lgkmcnt(5)
	v_mfma_f32_32x32x16_bf16 v[64:79], v[192:195], v[136:139], v[64:79]
	ds_read_b128 v[192:195], v96 offset:23552
	v_fmamk_f32 v167, v230, 0x3dd53b94, v110
	v_fmamk_f32 v168, v231, 0x3dd53b94, v110
	v_fmamk_f32 v169, v232, 0x3dd53b94, v110
	v_fmac_f32_e32 v110, 0x3dd53b94, v233
	v_cvt_pk_bf16_f32 v220, v222, v223
	s_waitcnt lgkmcnt(5)
	v_mfma_f32_32x32x16_bf16 v[64:79], v[198:201], v[140:143], v[64:79]
	ds_read_b128 v[198:201], v96 offset:24576
	v_cvt_pk_bf16_f32 v221, v224, v225
	v_exp_f32_e32 v159, v159
	v_exp_f32_e32 v111, v111
	s_waitcnt lgkmcnt(5)
	v_mfma_f32_32x32x16_bf16 v[64:79], v[202:205], v[144:147], v[64:79]
	ds_read_b128 v[202:205], v96 offset:25600
	v_mfma_f32_32x32x16_bf16 v[48:63], v[148:151], v[218:221], v[48:63]
	ds_read_b128 v[148:151], v96 offset:12288
	v_exp_f32_e32 v165, v165
	v_exp_f32_e32 v166, v166
	v_exp_f32_e32 v167, v167
	v_mfma_f32_32x32x16_bf16 v[32:47], v[106:109], v[218:221], v[32:47]
	ds_read_b128 v[106:109], v96 offset:13312
	v_exp_f32_e32 v168, v168
	v_exp_f32_e32 v169, v169
	v_exp_f32_e32 v110, v110
	v_mfma_f32_32x32x16_bf16 v[16:31], v[98:101], v[218:221], v[16:31]
	v_cvt_pk_bf16_f32 v98, v159, v111
	v_cvt_pk_bf16_f32 v99, v165, v166
	v_cvt_pk_bf16_f32 v100, v167, v168
	v_cvt_pk_bf16_f32 v101, v169, v110
	v_mfma_f32_32x32x16_bf16 v[0:15], v[102:105], v[218:221], v[0:15]
	ds_read_b128 v[102:105], v96 offset:15360
	v_add_f32_e32 v183, v159, v183
	v_add_f32_e32 v183, v111, v183
	v_add_f32_e32 v183, v165, v183
	v_mfma_f32_32x32x16_bf16 v[48:63], v[234:237], v[98:101], v[48:63]
	v_add_f32_e32 v183, v166, v183
	v_add_f32_e32 v183, v167, v183
	v_add_f32_e32 v183, v168, v183
	v_mfma_f32_32x32x16_bf16 v[32:47], v[206:209], v[98:101], v[32:47]
	v_add_f32_e32 v183, v169, v183
	v_add_f32_e32 v183, v110, v183
	v_mfma_f32_32x32x16_bf16 v[16:31], v[238:241], v[98:101], v[16:31]
	v_add_f32_e32 v81, v81, v183
	v_mfma_f32_32x32x16_bf16 v[0:15], v[242:245], v[98:101], v[0:15]
	ds_read_b128 v[98:101], v96 offset:14336
	s_branch .Lmy_join

.Lmy_nodma:
	s_waitcnt lgkmcnt(9)
	v_mfma_f32_32x32x16_bf16 v[218:233], v[172:175], v[82:85], 0
	ds_read_b128 v[172:175], v96 offset:26624
	v_max_f32_e32 v159, v64, v65
	v_max3_f32 v159, v159, v66, v67
	v_max3_f32 v159, v159, v68, v69
	v_max3_f32 v159, v159, v70, v71
	s_waitcnt lgkmcnt(9)
	v_mfma_f32_32x32x16_bf16 v[218:233], v[176:179], v[86:89], v[218:233]
	ds_read_b128 v[176:179], v96 offset:27648
	v_max3_f32 v159, v159, v72, v73
	v_max3_f32 v159, v159, v74, v75
	v_max3_f32 v159, v159, v76, v77
	v_max3_f32 v159, v159, v78, v79
	s_waitcnt lgkmcnt(9)
	v_mfma_f32_32x32x16_bf16 v[218:233], v[188:191], v[90:93], v[218:233]
	ds_read_b128 v[188:191], v96 offset:28672
	v_mul_f32_e32 v111, 0x3dd53b94, v159
	v_add_f32_e32 v110, 0x41000000, v80
	v_cmp_le_f32_e32 vcc, v111, v110
	s_cmp_eq_u64 vcc, exec
	s_cbranch_scc1 .LBB0_788
	v_mov_b32_e32 v111, v159
	s_nop 1
	v_permlane32_swap_b32_e32 v159, v111
	v_max_f32_e32 v159, v159, v111
	v_mul_f32_e32 v111, 0x3dd53b94, v159
	v_max_f32_e32 v110, v111, v111
	v_max_f32_e32 v111, v80, v80
	v_max_f32_e32 v111, v111, v110
	v_sub_f32_e32 v80, v80, v111
	v_exp_f32_e32 v80, v80
	v_add_f32_e32 v110, 0x41000000, v111
	v_mul_f32_e32 v81, v81, v80
	v_pk_mul_f32 v[62:63], v[62:63], v[80:81] op_sel_hi:[1,0]
	v_pk_mul_f32 v[60:61], v[60:61], v[80:81] op_sel_hi:[1,0]
	v_pk_mul_f32 v[58:59], v[58:59], v[80:81] op_sel_hi:[1,0]
	v_pk_mul_f32 v[56:57], v[56:57], v[80:81] op_sel_hi:[1,0]
	v_pk_mul_f32 v[54:55], v[54:55], v[80:81] op_sel_hi:[1,0]
	v_pk_mul_f32 v[52:53], v[52:53], v[80:81] op_sel_hi:[1,0]
	v_pk_mul_f32 v[50:51], v[50:51], v[80:81] op_sel_hi:[1,0]
	v_pk_mul_f32 v[48:49], v[48:49], v[80:81] op_sel_hi:[1,0]
	v_pk_mul_f32 v[46:47], v[46:47], v[80:81] op_sel_hi:[1,0]
	v_pk_mul_f32 v[44:45], v[44:45], v[80:81] op_sel_hi:[1,0]
	v_pk_mul_f32 v[42:43], v[42:43], v[80:81] op_sel_hi:[1,0]
	v_pk_mul_f32 v[40:41], v[40:41], v[80:81] op_sel_hi:[1,0]
	v_pk_mul_f32 v[38:39], v[38:39], v[80:81] op_sel_hi:[1,0]
	v_pk_mul_f32 v[36:37], v[36:37], v[80:81] op_sel_hi:[1,0]
	v_pk_mul_f32 v[34:35], v[34:35], v[80:81] op_sel_hi:[1,0]
	v_pk_mul_f32 v[32:33], v[32:33], v[80:81] op_sel_hi:[1,0]
	v_pk_mul_f32 v[30:31], v[30:31], v[80:81] op_sel_hi:[1,0]
	v_pk_mul_f32 v[28:29], v[28:29], v[80:81] op_sel_hi:[1,0]
	v_pk_mul_f32 v[26:27], v[26:27], v[80:81] op_sel_hi:[1,0]
	v_pk_mul_f32 v[24:25], v[24:25], v[80:81] op_sel_hi:[1,0]
	v_pk_mul_f32 v[22:23], v[22:23], v[80:81] op_sel_hi:[1,0]
	v_pk_mul_f32 v[20:21], v[20:21], v[80:81] op_sel_hi:[1,0]
	v_pk_mul_f32 v[18:19], v[18:19], v[80:81] op_sel_hi:[1,0]
	v_pk_mul_f32 v[16:17], v[16:17], v[80:81] op_sel_hi:[1,0]
	v_pk_mul_f32 v[14:15], v[14:15], v[80:81] op_sel_hi:[1,0]
	v_pk_mul_f32 v[12:13], v[12:13], v[80:81] op_sel_hi:[1,0]
	v_pk_mul_f32 v[10:11], v[10:11], v[80:81] op_sel_hi:[1,0]
	v_pk_mul_f32 v[8:9], v[8:9], v[80:81] op_sel_hi:[1,0]
	v_pk_mul_f32 v[6:7], v[6:7], v[80:81] op_sel_hi:[1,0]
	v_pk_mul_f32 v[4:5], v[4:5], v[80:81] op_sel_hi:[1,0]
	v_pk_mul_f32 v[2:3], v[2:3], v[80:81] op_sel_hi:[1,0]
	v_pk_mul_f32 v[0:1], v[0:1], v[80:81] op_sel_hi:[1,0]
	v_mov_b32_e32 v80, v111
.LBB0_788:
	s_waitcnt lgkmcnt(9)
	v_mfma_f32_32x32x16_bf16 v[218:233], v[192:195], v[112:115], v[218:233]
	ds_read_b128 v[192:195], v96 offset:29696
	v_fma_f32 v64, v64, s80, -v80
	v_fma_f32 v65, v65, s80, -v80
	v_exp_f32_e32 v64, v64
	v_fma_f32 v66, v66, s80, -v80
	v_exp_f32_e32 v65, v65
	s_waitcnt lgkmcnt(9)
	v_mfma_f32_32x32x16_bf16 v[218:233], v[198:201], v[116:119], v[218:233]
	ds_read_b128 v[198:201], v96 offset:30720
	v_add_f32_e32 v183, 0, v64
	v_fma_f32 v67, v67, s80, -v80
	v_exp_f32_e32 v66, v66
	v_add_f32_e32 v183, v65, v183
	v_fma_f32 v68, v68, s80, -v80
	s_waitcnt lgkmcnt(9)
	v_mfma_f32_32x32x16_bf16 v[218:233], v[202:205], v[120:123], v[218:233]
	ds_read_b128 v[202:205], v96 offset:31744
	v_exp_f32_e32 v67, v67
	v_add_f32_e32 v183, v66, v183
	v_fma_f32 v69, v69, s80, -v80
	v_exp_f32_e32 v68, v68
	v_add_f32_e32 v183, v67, v183
	s_waitcnt lgkmcnt(5)
	v_mfma_f32_32x32x16_bf16 v[218:233], v[172:175], v[124:127], v[218:233]
	v_fma_f32 v70, v70, s80, -v80
	v_exp_f32_e32 v69, v69
	v_add_f32_e32 v183, v68, v183
	v_fma_f32 v71, v71, s80, -v80
	v_exp_f32_e32 v70, v70
	s_waitcnt lgkmcnt(4)
	v_mfma_f32_32x32x16_bf16 v[218:233], v[176:179], v[128:131], v[218:233]
	v_add_f32_e32 v183, v69, v183
	v_exp_f32_e32 v71, v71
	v_add_f32_e32 v183, v70, v183
	v_add_f32_e32 v183, v71, v183
	v_fma_f32 v159, v72, s80, -v80
	s_waitcnt lgkmcnt(3)
	v_mfma_f32_32x32x16_bf16 v[218:233], v[188:191], v[132:135], v[218:233]
	v_fma_f32 v111, v73, s80, -v80
	v_fma_f32 v165, v74, s80, -v80
	v_fma_f32 v166, v75, s80, -v80
	v_cvt_pk_bf16_f32 v64, v64, v65
	v_cvt_pk_bf16_f32 v65, v66, v67
	s_waitcnt lgkmcnt(2)
	v_mfma_f32_32x32x16_bf16 v[218:233], v[192:195], v[136:139], v[218:233]
	v_fma_f32 v167, v76, s80, -v80
	v_fma_f32 v168, v77, s80, -v80
	v_fma_f32 v169, v78, s80, -v80
	v_fma_f32 v170, v79, s80, -v80
	v_cvt_pk_bf16_f32 v66, v68, v69
	s_waitcnt lgkmcnt(1)
	v_mfma_f32_32x32x16_bf16 v[218:233], v[198:201], v[140:143], v[218:233]
	v_cvt_pk_bf16_f32 v67, v70, v71
	v_exp_f32_e32 v159, v159
	v_exp_f32_e32 v111, v111
	s_waitcnt lgkmcnt(0)
	v_mfma_f32_32x32x16_bf16 v[218:233], v[202:205], v[144:147], v[218:233]
	s_waitcnt lgkmcnt(9)
	v_mfma_f32_32x32x16_bf16 v[48:63], v[148:151], v[64:67], v[48:63]
	ds_read_b128 v[234:237], v96 offset:16384
	ds_read_b128 v[68:71], v96 offset:17408
	ds_read_b128 v[72:75], v96 offset:18432
	ds_read_b128 v[76:79], v96 offset:19456
	ds_read_b128 v[148:151], v96 offset:32768
	v_exp_f32_e32 v165, v165
	v_exp_f32_e32 v166, v166
	v_exp_f32_e32 v167, v167
	s_waitcnt lgkmcnt(13)
	v_mfma_f32_32x32x16_bf16 v[32:47], v[106:109], v[64:67], v[32:47]
	ds_read_b128 v[106:109], v96 offset:33792
	v_exp_f32_e32 v168, v168
	v_exp_f32_e32 v169, v169
	v_exp_f32_e32 v170, v170
	s_waitcnt lgkmcnt(12)
	v_mfma_f32_32x32x16_bf16 v[16:31], v[98:101], v[64:67], v[16:31]
	v_cvt_pk_bf16_f32 v98, v159, v111
	v_cvt_pk_bf16_f32 v99, v165, v166
	v_cvt_pk_bf16_f32 v100, v167, v168
	v_cvt_pk_bf16_f32 v101, v169, v170
	s_waitcnt lgkmcnt(13)
	v_mfma_f32_32x32x16_bf16 v[0:15], v[102:105], v[64:67], v[0:15]
	ds_read_b128 v[102:105], v96 offset:35840
	ds_read_b128 v[206:209], v96 offset:37888
	ds_read_b128 v[238:241], v96 offset:38912
	ds_read_b128 v[242:245], v96 offset:39936
	v_add_f32_e32 v183, v159, v183
	v_add_f32_e32 v183, v111, v183
	v_add_f32_e32 v183, v165, v183
	s_waitcnt lgkmcnt(9)
	v_mfma_f32_32x32x16_bf16 v[48:63], v[234:237], v[98:101], v[48:63]
	ds_read_b128 v[234:237], v96 offset:36864
	v_add_f32_e32 v183, v166, v183
	v_add_f32_e32 v183, v167, v183
	v_add_f32_e32 v183, v168, v183
	s_waitcnt lgkmcnt(9)
	v_mfma_f32_32x32x16_bf16 v[32:47], v[68:71], v[98:101], v[32:47]
	v_add_f32_e32 v183, v169, v183
	v_add_f32_e32 v183, v170, v183
	s_waitcnt lgkmcnt(8)
	v_mfma_f32_32x32x16_bf16 v[16:31], v[72:75], v[98:101], v[16:31]
	v_add_f32_e32 v81, v81, v183
	s_waitcnt lgkmcnt(7)
	v_mfma_f32_32x32x16_bf16 v[0:15], v[76:79], v[98:101], v[0:15]
	ds_read_b128 v[98:101], v96 offset:34816
	v_lshl_add_u64 v[160:161], v[160:161], 0, s[26:27]
	v_lshl_add_u64 v[162:163], v[162:163], 0, s[28:29]
	s_cmp_eq_u32 s5, 34
	s_cbranch_scc1 .Lmy_exit
	s_mov_b32 s2, s5
	s_branch .LBB0_784
.Lmy_exit:
	s_waitcnt lgkmcnt(0)
	v_max_f32_e32 v111, v218, v219
	v_max3_f32 v111, v111, v220, v221
	v_max3_f32 v111, v111, v222, v223
	v_max3_f32 v111, v111, v224, v225
	v_max3_f32 v111, v111, v226, v227
	v_max3_f32 v111, v111, v228, v229
	v_max3_f32 v111, v111, v230, v231
	v_max3_f32 v111, v111, v232, v233
	v_mul_f32_e32 v159, 0x3dd53b94, v111
	v_cmp_le_f32_e32 vcc, v159, v110
	s_cmp_eq_u64 vcc, exec
	s_cbranch_scc1 .Lmy_x790
	v_mov_b32_e32 v159, v111
	s_nop 1
	v_permlane32_swap_b32_e32 v111, v159
	v_max_f32_e32 v111, v111, v159
	v_mul_f32_e32 v111, 0x3dd53b94, v111
	v_max_f32_e32 v110, v111, v111
	v_max_f32_e32 v111, v80, v80
	v_max_f32_e32 v111, v111, v110
	v_sub_f32_e32 v80, v80, v111
	v_exp_f32_e32 v80, v80
	v_xor_b32_e32 v110, 0x80000000, v111
	v_mul_f32_e32 v81, v81, v80
	v_pk_mul_f32 v[62:63], v[62:63], v[80:81] op_sel_hi:[1,0]
	v_pk_mul_f32 v[60:61], v[60:61], v[80:81] op_sel_hi:[1,0]
	v_pk_mul_f32 v[58:59], v[58:59], v[80:81] op_sel_hi:[1,0]
	v_pk_mul_f32 v[56:57], v[56:57], v[80:81] op_sel_hi:[1,0]
	v_pk_mul_f32 v[54:55], v[54:55], v[80:81] op_sel_hi:[1,0]
	v_pk_mul_f32 v[52:53], v[52:53], v[80:81] op_sel_hi:[1,0]
	v_pk_mul_f32 v[50:51], v[50:51], v[80:81] op_sel_hi:[1,0]
	v_pk_mul_f32 v[48:49], v[48:49], v[80:81] op_sel_hi:[1,0]
	v_pk_mul_f32 v[46:47], v[46:47], v[80:81] op_sel_hi:[1,0]
	v_pk_mul_f32 v[44:45], v[44:45], v[80:81] op_sel_hi:[1,0]
	v_pk_mul_f32 v[42:43], v[42:43], v[80:81] op_sel_hi:[1,0]
	v_pk_mul_f32 v[40:41], v[40:41], v[80:81] op_sel_hi:[1,0]
	v_pk_mul_f32 v[38:39], v[38:39], v[80:81] op_sel_hi:[1,0]
	v_pk_mul_f32 v[36:37], v[36:37], v[80:81] op_sel_hi:[1,0]
	v_pk_mul_f32 v[34:35], v[34:35], v[80:81] op_sel_hi:[1,0]
	v_pk_mul_f32 v[32:33], v[32:33], v[80:81] op_sel_hi:[1,0]
	v_pk_mul_f32 v[30:31], v[30:31], v[80:81] op_sel_hi:[1,0]
	v_pk_mul_f32 v[28:29], v[28:29], v[80:81] op_sel_hi:[1,0]
	v_pk_mul_f32 v[26:27], v[26:27], v[80:81] op_sel_hi:[1,0]
	v_pk_mul_f32 v[24:25], v[24:25], v[80:81] op_sel_hi:[1,0]
	v_pk_mul_f32 v[22:23], v[22:23], v[80:81] op_sel_hi:[1,0]
	v_pk_mul_f32 v[20:21], v[20:21], v[80:81] op_sel_hi:[1,0]
	v_pk_mul_f32 v[18:19], v[18:19], v[80:81] op_sel_hi:[1,0]
	v_pk_mul_f32 v[16:17], v[16:17], v[80:81] op_sel_hi:[1,0]
	v_pk_mul_f32 v[14:15], v[14:15], v[80:81] op_sel_hi:[1,0]
	v_pk_mul_f32 v[12:13], v[12:13], v[80:81] op_sel_hi:[1,0]
	v_pk_mul_f32 v[10:11], v[10:11], v[80:81] op_sel_hi:[1,0]
	v_pk_mul_f32 v[8:9], v[8:9], v[80:81] op_sel_hi:[1,0]
	v_pk_mul_f32 v[6:7], v[6:7], v[80:81] op_sel_hi:[1,0]
	v_pk_mul_f32 v[4:5], v[4:5], v[80:81] op_sel_hi:[1,0]
	v_pk_mul_f32 v[2:3], v[2:3], v[80:81] op_sel_hi:[1,0]
	v_pk_mul_f32 v[0:1], v[0:1], v[80:81] op_sel_hi:[1,0]
	v_mov_b32_e32 v80, v111
	s_branch .Lmy_x791

.Lmy_x791:
	v_fmamk_f32 v218, v218, 0x3dd53b94, v110
	v_fmamk_f32 v219, v219, 0x3dd53b94, v110
	v_exp_f32_e32 v218, v218
	v_fmamk_f32 v220, v220, 0x3dd53b94, v110
	v_exp_f32_e32 v219, v219
	v_add_f32_e32 v183, 0, v218
	v_fmamk_f32 v221, v221, 0x3dd53b94, v110
	v_exp_f32_e32 v220, v220
	v_add_f32_e32 v183, v219, v183
	v_fmamk_f32 v222, v222, 0x3dd53b94, v110
	v_exp_f32_e32 v221, v221
	v_add_f32_e32 v183, v220, v183
	v_fmamk_f32 v223, v223, 0x3dd53b94, v110
	v_exp_f32_e32 v222, v222
	v_add_f32_e32 v183, v221, v183
	v_fmamk_f32 v224, v224, 0x3dd53b94, v110
	v_exp_f32_e32 v223, v223
	v_add_f32_e32 v183, v222, v183
	v_fmamk_f32 v225, v225, 0x3dd53b94, v110
	v_exp_f32_e32 v224, v224
	v_add_f32_e32 v183, v223, v183
	v_exp_f32_e32 v225, v225
	v_add_f32_e32 v183, v224, v183
	v_add_f32_e32 v183, v225, v183
	v_fmamk_f32 v159, v226, 0x3dd53b94, v110
	v_fmamk_f32 v111, v227, 0x3dd53b94, v110
	v_fmamk_f32 v165, v228, 0x3dd53b94, v110
	v_fmamk_f32 v166, v229, 0x3dd53b94, v110
	v_cvt_pk_bf16_f32 v218, v218, v219
	v_cvt_pk_bf16_f32 v219, v220, v221
	v_fmamk_f32 v167, v230, 0x3dd53b94, v110
	v_fmamk_f32 v168, v231, 0x3dd53b94, v110
	v_fmamk_f32 v169, v232, 0x3dd53b94, v110
	v_fmac_f32_e32 v110, 0x3dd53b94, v233
	v_cvt_pk_bf16_f32 v220, v222, v223
	v_cvt_pk_bf16_f32 v221, v224, v225
	v_exp_f32_e32 v159, v159
	v_exp_f32_e32 v111, v111
	v_mfma_f32_32x32x16_bf16 v[48:63], v[148:151], v[218:221], v[48:63]
	v_exp_f32_e32 v165, v165
	v_exp_f32_e32 v166, v166
	v_exp_f32_e32 v167, v167
	v_mfma_f32_32x32x16_bf16 v[32:47], v[106:109], v[218:221], v[32:47]
	v_exp_f32_e32 v168, v168
	v_exp_f32_e32 v169, v169
	v_exp_f32_e32 v110, v110
	v_mfma_f32_32x32x16_bf16 v[16:31], v[98:101], v[218:221], v[16:31]
	v_cvt_pk_bf16_f32 v98, v159, v111
	v_cvt_pk_bf16_f32 v99, v165, v166
	v_cvt_pk_bf16_f32 v100, v167, v168
	v_cvt_pk_bf16_f32 v101, v169, v110
	v_mfma_f32_32x32x16_bf16 v[0:15], v[102:105], v[218:221], v[0:15]
	v_add_f32_e32 v183, v159, v183
	v_add_f32_e32 v183, v111, v183
	v_add_f32_e32 v183, v165, v183
	v_mfma_f32_32x32x16_bf16 v[48:63], v[234:237], v[98:101], v[48:63]
	v_add_f32_e32 v183, v166, v183
	v_add_f32_e32 v183, v167, v183
	v_add_f32_e32 v183, v168, v183
	v_mfma_f32_32x32x16_bf16 v[32:47], v[206:209], v[98:101], v[32:47]
	v_add_f32_e32 v183, v169, v183
	v_add_f32_e32 v183, v110, v183
	v_mfma_f32_32x32x16_bf16 v[16:31], v[238:241], v[98:101], v[16:31]
	v_add_f32_e32 v81, v81, v183
	v_mfma_f32_32x32x16_bf16 v[0:15], v[242:245], v[98:101], v[0:15]
	v_mov_b32_e32 v171, v81
	s_nop 1
	v_permlane32_swap_b32_e32 v81, v171
	v_add_f32_e32 v81, v81, v171
	s_nop 0
	s_nop 0
	s_nop 0
	s_nop 0
	s_nop 0
	s_nop 0
	s_nop 0
	s_nop 0
	s_nop 0
	s_nop 0
	s_nop 0
	s_nop 0
	s_nop 0
	s_nop 0
